# idx scheduled compaction survivor write-out as straight VALU (v_mbcnt prefix, VGPR running count, dead-slot dump) instead of 16 VALU-SALU serialized steps; plus c3
# baseline (speedup 1.0000x reference)
; __device__ __forceinline__ unsigned compact1024(unsigned* base, int n, int lane, int lowbit, int& newcnt) {
;     unsigned e[16];
; #pragma unroll
;     for (int j = 0; j < 16; ++j) { const int i = j * 64 + lane; e[j] = i < n ? base[i] : 0u; }
;     const unsigned tau = select_kth<16>(e, 256, lowbit);
;     const u64 lt = (1ull << lane) - 1ull; int run = 0;
; #pragma unroll
;     for (int j = 0; j < 16; ++j) { const bool p = e[j] >= tau; const u64 m = __ballot(p); if (p) base[run + __popcll(m & lt)] = e[j]; run += __popcll(m); }
;     newcnt = run;
.LBB0_1267:
	s_or_b64 exec, exec, s[0:1]
	v_mov_b32_e32 v53, 0
	v_mov_b32_e32 v56, s92
	v_add_u32_e32 v56, 0xffc, v56
	v_cmp_ge_u32_e32 vcc, v34, v48
	s_nop 1
	v_mbcnt_lo_u32_b32 v54, vcc_lo, v53
	v_mbcnt_hi_u32_b32 v54, vcc_hi, v54
	v_lshl_add_u32 v55, v54, 2, s92
	v_cndmask_b32_e32 v55, v56, v55, vcc
	ds_write_b32 v55, v34
	v_bcnt_u32_b32 v54, vcc_lo, v53
	v_bcnt_u32_b32 v53, vcc_hi, v54
	v_cmp_ge_u32_e32 vcc, v35, v48
	s_nop 1
	v_mbcnt_lo_u32_b32 v54, vcc_lo, v53
	v_mbcnt_hi_u32_b32 v54, vcc_hi, v54
	v_lshl_add_u32 v55, v54, 2, s92
	v_cndmask_b32_e32 v55, v56, v55, vcc
	ds_write_b32 v55, v35
	v_bcnt_u32_b32 v54, vcc_lo, v53
	v_bcnt_u32_b32 v53, vcc_hi, v54
	v_cmp_ge_u32_e32 vcc, v32, v48
	s_nop 1
	v_mbcnt_lo_u32_b32 v54, vcc_lo, v53
	v_mbcnt_hi_u32_b32 v54, vcc_hi, v54
	v_lshl_add_u32 v55, v54, 2, s92
	v_cndmask_b32_e32 v55, v56, v55, vcc
	ds_write_b32 v55, v32
	v_bcnt_u32_b32 v54, vcc_lo, v53
	v_bcnt_u32_b32 v53, vcc_hi, v54
	v_cmp_ge_u32_e32 vcc, v33, v48
	s_nop 1
	v_mbcnt_lo_u32_b32 v54, vcc_lo, v53
	v_mbcnt_hi_u32_b32 v54, vcc_hi, v54
	v_lshl_add_u32 v55, v54, 2, s92
	v_cndmask_b32_e32 v55, v56, v55, vcc
	ds_write_b32 v55, v33
	v_bcnt_u32_b32 v54, vcc_lo, v53
	v_bcnt_u32_b32 v53, vcc_hi, v54
	v_cmp_ge_u32_e32 vcc, v47, v48
	s_nop 1
	v_mbcnt_lo_u32_b32 v54, vcc_lo, v53
	v_mbcnt_hi_u32_b32 v54, vcc_hi, v54
	v_lshl_add_u32 v55, v54, 2, s92
	v_cndmask_b32_e32 v55, v56, v55, vcc
	ds_write_b32 v55, v47
	v_bcnt_u32_b32 v54, vcc_lo, v53
	v_bcnt_u32_b32 v53, vcc_hi, v54
	v_cmp_ge_u32_e32 vcc, v45, v48
	s_nop 1
	v_mbcnt_lo_u32_b32 v54, vcc_lo, v53
	v_mbcnt_hi_u32_b32 v54, vcc_hi, v54
	v_lshl_add_u32 v55, v54, 2, s92
	v_cndmask_b32_e32 v55, v56, v55, vcc
	ds_write_b32 v55, v45
	v_bcnt_u32_b32 v54, vcc_lo, v53
	v_bcnt_u32_b32 v53, vcc_hi, v54
	v_cmp_ge_u32_e32 vcc, v46, v48
	s_nop 1
	v_mbcnt_lo_u32_b32 v54, vcc_lo, v53
	v_mbcnt_hi_u32_b32 v54, vcc_hi, v54
	v_lshl_add_u32 v55, v54, 2, s92
	v_cndmask_b32_e32 v55, v56, v55, vcc
	ds_write_b32 v55, v46
	v_bcnt_u32_b32 v54, vcc_lo, v53
	v_bcnt_u32_b32 v53, vcc_hi, v54
	v_cmp_ge_u32_e32 vcc, v43, v48
	s_nop 1
	v_mbcnt_lo_u32_b32 v54, vcc_lo, v53
	v_mbcnt_hi_u32_b32 v54, vcc_hi, v54
	v_lshl_add_u32 v55, v54, 2, s92
	v_cndmask_b32_e32 v55, v56, v55, vcc
	ds_write_b32 v55, v43
	v_bcnt_u32_b32 v54, vcc_lo, v53
	v_bcnt_u32_b32 v53, vcc_hi, v54
	v_cmp_ge_u32_e32 vcc, v44, v48
	s_nop 1
	v_mbcnt_lo_u32_b32 v54, vcc_lo, v53
	v_mbcnt_hi_u32_b32 v54, vcc_hi, v54
	v_lshl_add_u32 v55, v54, 2, s92
	v_cndmask_b32_e32 v55, v56, v55, vcc
	ds_write_b32 v55, v44
	v_bcnt_u32_b32 v54, vcc_lo, v53
	v_bcnt_u32_b32 v53, vcc_hi, v54
	v_cmp_ge_u32_e32 vcc, v41, v48
	s_nop 1
	v_mbcnt_lo_u32_b32 v54, vcc_lo, v53
	v_mbcnt_hi_u32_b32 v54, vcc_hi, v54
	v_lshl_add_u32 v55, v54, 2, s92
	v_cndmask_b32_e32 v55, v56, v55, vcc
	ds_write_b32 v55, v41
	v_bcnt_u32_b32 v54, vcc_lo, v53
	v_bcnt_u32_b32 v53, vcc_hi, v54
	v_cmp_ge_u32_e32 vcc, v42, v48
	s_nop 1
	v_mbcnt_lo_u32_b32 v54, vcc_lo, v53
	v_mbcnt_hi_u32_b32 v54, vcc_hi, v54
	v_lshl_add_u32 v55, v54, 2, s92
	v_cndmask_b32_e32 v55, v56, v55, vcc
	ds_write_b32 v55, v42
	v_bcnt_u32_b32 v54, vcc_lo, v53
	v_bcnt_u32_b32 v53, vcc_hi, v54
	v_cmp_ge_u32_e32 vcc, v39, v48
	s_nop 1
	v_mbcnt_lo_u32_b32 v54, vcc_lo, v53
	v_mbcnt_hi_u32_b32 v54, vcc_hi, v54
	v_lshl_add_u32 v55, v54, 2, s92
	v_cndmask_b32_e32 v55, v56, v55, vcc
	ds_write_b32 v55, v39
	v_bcnt_u32_b32 v54, vcc_lo, v53
	v_bcnt_u32_b32 v53, vcc_hi, v54
	v_cmp_ge_u32_e32 vcc, v40, v48
	s_nop 1
	v_mbcnt_lo_u32_b32 v54, vcc_lo, v53
	v_mbcnt_hi_u32_b32 v54, vcc_hi, v54
	v_lshl_add_u32 v55, v54, 2, s92
	v_cndmask_b32_e32 v55, v56, v55, vcc
	ds_write_b32 v55, v40
	v_bcnt_u32_b32 v54, vcc_lo, v53
	v_bcnt_u32_b32 v53, vcc_hi, v54
	v_cmp_ge_u32_e32 vcc, v37, v48
	s_nop 1
	v_mbcnt_lo_u32_b32 v54, vcc_lo, v53
	v_mbcnt_hi_u32_b32 v54, vcc_hi, v54
	v_lshl_add_u32 v55, v54, 2, s92
	v_cndmask_b32_e32 v55, v56, v55, vcc
	ds_write_b32 v55, v37
	v_bcnt_u32_b32 v54, vcc_lo, v53
	v_bcnt_u32_b32 v53, vcc_hi, v54
	v_cmp_ge_u32_e32 vcc, v38, v48
	s_nop 1
	v_mbcnt_lo_u32_b32 v54, vcc_lo, v53
	v_mbcnt_hi_u32_b32 v54, vcc_hi, v54
	v_lshl_add_u32 v55, v54, 2, s92
	v_cndmask_b32_e32 v55, v56, v55, vcc
	ds_write_b32 v55, v38
	v_bcnt_u32_b32 v54, vcc_lo, v53
	v_bcnt_u32_b32 v53, vcc_hi, v54
	v_cmp_ge_u32_e32 vcc, v36, v48
	s_nop 1
	v_mbcnt_lo_u32_b32 v54, vcc_lo, v53
	v_mbcnt_hi_u32_b32 v54, vcc_hi, v54
	v_lshl_add_u32 v55, v54, 2, s92
	v_cndmask_b32_e32 v55, v56, v55, vcc
	ds_write_b32 v55, v36
	v_bcnt_u32_b32 v54, vcc_lo, v53
	v_bcnt_u32_b32 v53, vcc_hi, v54
	s_nop 0
	v_readfirstlane_b32 s2, v53
	s_nop 1
	s_and_saveexec_b64 s[0:1], s[4:5]
	v_mov_b32_e32 v132, s2
	v_mov_b32_e32 v247, v48
	s_or_b64 exec, exec, s[0:1]

; __device__ __forceinline__ unsigned compact1024(unsigned* base, int n, int lane, int lowbit, int& newcnt) {
;     unsigned e[16];
; #pragma unroll
;     for (int j = 0; j < 16; ++j) { const int i = j * 64 + lane; e[j] = i < n ? base[i] : 0u; }
;     const unsigned tau = select_kth<16>(e, 256, lowbit);
;     const u64 lt = (1ull << lane) - 1ull; int run = 0;
; #pragma unroll
;     for (int j = 0; j < 16; ++j) { const bool p = e[j] >= tau; const u64 m = __ballot(p); if (p) base[run + __popcll(m & lt)] = e[j]; run += __popcll(m); }
;     newcnt = run;
.LBB0_1331:
	s_or_b64 exec, exec, s[0:1]
	v_mov_b32_e32 v53, 0
	v_mov_b32_e32 v56, s92
	v_add_u32_e32 v56, 0xffc, v56
	v_cmp_ge_u32_e32 vcc, v34, v48
	s_nop 1
	v_mbcnt_lo_u32_b32 v54, vcc_lo, v53
	v_mbcnt_hi_u32_b32 v54, vcc_hi, v54
	v_lshl_add_u32 v55, v54, 2, s92
	v_cndmask_b32_e32 v55, v56, v55, vcc
	ds_write_b32 v55, v34 offset:4096
	v_bcnt_u32_b32 v54, vcc_lo, v53
	v_bcnt_u32_b32 v53, vcc_hi, v54
	v_cmp_ge_u32_e32 vcc, v35, v48
	s_nop 1
	v_mbcnt_lo_u32_b32 v54, vcc_lo, v53
	v_mbcnt_hi_u32_b32 v54, vcc_hi, v54
	v_lshl_add_u32 v55, v54, 2, s92
	v_cndmask_b32_e32 v55, v56, v55, vcc
	ds_write_b32 v55, v35 offset:4096
	v_bcnt_u32_b32 v54, vcc_lo, v53
	v_bcnt_u32_b32 v53, vcc_hi, v54
	v_cmp_ge_u32_e32 vcc, v32, v48
	s_nop 1
	v_mbcnt_lo_u32_b32 v54, vcc_lo, v53
	v_mbcnt_hi_u32_b32 v54, vcc_hi, v54
	v_lshl_add_u32 v55, v54, 2, s92
	v_cndmask_b32_e32 v55, v56, v55, vcc
	ds_write_b32 v55, v32 offset:4096
	v_bcnt_u32_b32 v54, vcc_lo, v53
	v_bcnt_u32_b32 v53, vcc_hi, v54
	v_cmp_ge_u32_e32 vcc, v33, v48
	s_nop 1
	v_mbcnt_lo_u32_b32 v54, vcc_lo, v53
	v_mbcnt_hi_u32_b32 v54, vcc_hi, v54
	v_lshl_add_u32 v55, v54, 2, s92
	v_cndmask_b32_e32 v55, v56, v55, vcc
	ds_write_b32 v55, v33 offset:4096
	v_bcnt_u32_b32 v54, vcc_lo, v53
	v_bcnt_u32_b32 v53, vcc_hi, v54
	v_cmp_ge_u32_e32 vcc, v47, v48
	s_nop 1
	v_mbcnt_lo_u32_b32 v54, vcc_lo, v53
	v_mbcnt_hi_u32_b32 v54, vcc_hi, v54
	v_lshl_add_u32 v55, v54, 2, s92
	v_cndmask_b32_e32 v55, v56, v55, vcc
	ds_write_b32 v55, v47 offset:4096
	v_bcnt_u32_b32 v54, vcc_lo, v53
	v_bcnt_u32_b32 v53, vcc_hi, v54
	v_cmp_ge_u32_e32 vcc, v45, v48
	s_nop 1
	v_mbcnt_lo_u32_b32 v54, vcc_lo, v53
	v_mbcnt_hi_u32_b32 v54, vcc_hi, v54
	v_lshl_add_u32 v55, v54, 2, s92
	v_cndmask_b32_e32 v55, v56, v55, vcc
	ds_write_b32 v55, v45 offset:4096
	v_bcnt_u32_b32 v54, vcc_lo, v53
	v_bcnt_u32_b32 v53, vcc_hi, v54
	v_cmp_ge_u32_e32 vcc, v46, v48
	s_nop 1
	v_mbcnt_lo_u32_b32 v54, vcc_lo, v53
	v_mbcnt_hi_u32_b32 v54, vcc_hi, v54
	v_lshl_add_u32 v55, v54, 2, s92
	v_cndmask_b32_e32 v55, v56, v55, vcc
	ds_write_b32 v55, v46 offset:4096
	v_bcnt_u32_b32 v54, vcc_lo, v53
	v_bcnt_u32_b32 v53, vcc_hi, v54
	v_cmp_ge_u32_e32 vcc, v43, v48
	s_nop 1
	v_mbcnt_lo_u32_b32 v54, vcc_lo, v53
	v_mbcnt_hi_u32_b32 v54, vcc_hi, v54
	v_lshl_add_u32 v55, v54, 2, s92
	v_cndmask_b32_e32 v55, v56, v55, vcc
	ds_write_b32 v55, v43 offset:4096
	v_bcnt_u32_b32 v54, vcc_lo, v53
	v_bcnt_u32_b32 v53, vcc_hi, v54
	v_cmp_ge_u32_e32 vcc, v44, v48
	s_nop 1
	v_mbcnt_lo_u32_b32 v54, vcc_lo, v53
	v_mbcnt_hi_u32_b32 v54, vcc_hi, v54
	v_lshl_add_u32 v55, v54, 2, s92
	v_cndmask_b32_e32 v55, v56, v55, vcc
	ds_write_b32 v55, v44 offset:4096
	v_bcnt_u32_b32 v54, vcc_lo, v53
	v_bcnt_u32_b32 v53, vcc_hi, v54
	v_cmp_ge_u32_e32 vcc, v41, v48
	s_nop 1
	v_mbcnt_lo_u32_b32 v54, vcc_lo, v53
	v_mbcnt_hi_u32_b32 v54, vcc_hi, v54
	v_lshl_add_u32 v55, v54, 2, s92
	v_cndmask_b32_e32 v55, v56, v55, vcc
	ds_write_b32 v55, v41 offset:4096
	v_bcnt_u32_b32 v54, vcc_lo, v53
	v_bcnt_u32_b32 v53, vcc_hi, v54
	v_cmp_ge_u32_e32 vcc, v42, v48
	s_nop 1
	v_mbcnt_lo_u32_b32 v54, vcc_lo, v53
	v_mbcnt_hi_u32_b32 v54, vcc_hi, v54
	v_lshl_add_u32 v55, v54, 2, s92
	v_cndmask_b32_e32 v55, v56, v55, vcc
	ds_write_b32 v55, v42 offset:4096
	v_bcnt_u32_b32 v54, vcc_lo, v53
	v_bcnt_u32_b32 v53, vcc_hi, v54
	v_cmp_ge_u32_e32 vcc, v39, v48
	s_nop 1
	v_mbcnt_lo_u32_b32 v54, vcc_lo, v53
	v_mbcnt_hi_u32_b32 v54, vcc_hi, v54
	v_lshl_add_u32 v55, v54, 2, s92
	v_cndmask_b32_e32 v55, v56, v55, vcc
	ds_write_b32 v55, v39 offset:4096
	v_bcnt_u32_b32 v54, vcc_lo, v53
	v_bcnt_u32_b32 v53, vcc_hi, v54
	v_cmp_ge_u32_e32 vcc, v40, v48
	s_nop 1
	v_mbcnt_lo_u32_b32 v54, vcc_lo, v53
	v_mbcnt_hi_u32_b32 v54, vcc_hi, v54
	v_lshl_add_u32 v55, v54, 2, s92
	v_cndmask_b32_e32 v55, v56, v55, vcc
	ds_write_b32 v55, v40 offset:4096
	v_bcnt_u32_b32 v54, vcc_lo, v53
	v_bcnt_u32_b32 v53, vcc_hi, v54
	v_cmp_ge_u32_e32 vcc, v37, v48
	s_nop 1
	v_mbcnt_lo_u32_b32 v54, vcc_lo, v53
	v_mbcnt_hi_u32_b32 v54, vcc_hi, v54
	v_lshl_add_u32 v55, v54, 2, s92
	v_cndmask_b32_e32 v55, v56, v55, vcc
	ds_write_b32 v55, v37 offset:4096
	v_bcnt_u32_b32 v54, vcc_lo, v53
	v_bcnt_u32_b32 v53, vcc_hi, v54
	v_cmp_ge_u32_e32 vcc, v38, v48
	s_nop 1
	v_mbcnt_lo_u32_b32 v54, vcc_lo, v53
	v_mbcnt_hi_u32_b32 v54, vcc_hi, v54
	v_lshl_add_u32 v55, v54, 2, s92
	v_cndmask_b32_e32 v55, v56, v55, vcc
	ds_write_b32 v55, v38 offset:4096
	v_bcnt_u32_b32 v54, vcc_lo, v53
	v_bcnt_u32_b32 v53, vcc_hi, v54
	v_cmp_ge_u32_e32 vcc, v36, v48
	s_nop 1
	v_mbcnt_lo_u32_b32 v54, vcc_lo, v53
	v_mbcnt_hi_u32_b32 v54, vcc_hi, v54
	v_lshl_add_u32 v55, v54, 2, s92
	v_cndmask_b32_e32 v55, v56, v55, vcc
	ds_write_b32 v55, v36 offset:4096
	v_bcnt_u32_b32 v54, vcc_lo, v53
	v_bcnt_u32_b32 v53, vcc_hi, v54
	s_nop 0
	v_readfirstlane_b32 s2, v53
	s_nop 1
	s_and_saveexec_b64 s[0:1], s[6:7]
	v_mov_b32_e32 v132, s2
	v_mov_b32_e32 v247, v48
	s_or_b64 exec, exec, s[0:1]

; __device__ __forceinline__ unsigned compact1024(unsigned* base, int n, int lane, int lowbit, int& newcnt) {
;     unsigned e[16];
; #pragma unroll
;     for (int j = 0; j < 16; ++j) { const int i = j * 64 + lane; e[j] = i < n ? base[i] : 0u; }
;     const unsigned tau = select_kth<16>(e, 256, lowbit);
;     const u64 lt = (1ull << lane) - 1ull; int run = 0;
; #pragma unroll
;     for (int j = 0; j < 16; ++j) { const bool p = e[j] >= tau; const u64 m = __ballot(p); if (p) base[run + __popcll(m & lt)] = e[j]; run += __popcll(m); }
;     newcnt = run;
.LBB0_1395:
	s_or_b64 exec, exec, s[0:1]
	v_mov_b32_e32 v53, 0
	v_mov_b32_e32 v56, s92
	v_add_u32_e32 v56, 0xffc, v56
	v_cmp_ge_u32_e32 vcc, v34, v48
	s_nop 1
	v_mbcnt_lo_u32_b32 v54, vcc_lo, v53
	v_mbcnt_hi_u32_b32 v54, vcc_hi, v54
	v_lshl_add_u32 v55, v54, 2, s92
	v_cndmask_b32_e32 v55, v56, v55, vcc
	ds_write_b32 v55, v34 offset:8192
	v_bcnt_u32_b32 v54, vcc_lo, v53
	v_bcnt_u32_b32 v53, vcc_hi, v54
	v_cmp_ge_u32_e32 vcc, v35, v48
	s_nop 1
	v_mbcnt_lo_u32_b32 v54, vcc_lo, v53
	v_mbcnt_hi_u32_b32 v54, vcc_hi, v54
	v_lshl_add_u32 v55, v54, 2, s92
	v_cndmask_b32_e32 v55, v56, v55, vcc
	ds_write_b32 v55, v35 offset:8192
	v_bcnt_u32_b32 v54, vcc_lo, v53
	v_bcnt_u32_b32 v53, vcc_hi, v54
	v_cmp_ge_u32_e32 vcc, v32, v48
	s_nop 1
	v_mbcnt_lo_u32_b32 v54, vcc_lo, v53
	v_mbcnt_hi_u32_b32 v54, vcc_hi, v54
	v_lshl_add_u32 v55, v54, 2, s92
	v_cndmask_b32_e32 v55, v56, v55, vcc
	ds_write_b32 v55, v32 offset:8192
	v_bcnt_u32_b32 v54, vcc_lo, v53
	v_bcnt_u32_b32 v53, vcc_hi, v54
	v_cmp_ge_u32_e32 vcc, v33, v48
	s_nop 1
	v_mbcnt_lo_u32_b32 v54, vcc_lo, v53
	v_mbcnt_hi_u32_b32 v54, vcc_hi, v54
	v_lshl_add_u32 v55, v54, 2, s92
	v_cndmask_b32_e32 v55, v56, v55, vcc
	ds_write_b32 v55, v33 offset:8192
	v_bcnt_u32_b32 v54, vcc_lo, v53
	v_bcnt_u32_b32 v53, vcc_hi, v54
	v_cmp_ge_u32_e32 vcc, v47, v48
	s_nop 1
	v_mbcnt_lo_u32_b32 v54, vcc_lo, v53
	v_mbcnt_hi_u32_b32 v54, vcc_hi, v54
	v_lshl_add_u32 v55, v54, 2, s92
	v_cndmask_b32_e32 v55, v56, v55, vcc
	ds_write_b32 v55, v47 offset:8192
	v_bcnt_u32_b32 v54, vcc_lo, v53
	v_bcnt_u32_b32 v53, vcc_hi, v54
	v_cmp_ge_u32_e32 vcc, v45, v48
	s_nop 1
	v_mbcnt_lo_u32_b32 v54, vcc_lo, v53
	v_mbcnt_hi_u32_b32 v54, vcc_hi, v54
	v_lshl_add_u32 v55, v54, 2, s92
	v_cndmask_b32_e32 v55, v56, v55, vcc
	ds_write_b32 v55, v45 offset:8192
	v_bcnt_u32_b32 v54, vcc_lo, v53
	v_bcnt_u32_b32 v53, vcc_hi, v54
	v_cmp_ge_u32_e32 vcc, v46, v48
	s_nop 1
	v_mbcnt_lo_u32_b32 v54, vcc_lo, v53
	v_mbcnt_hi_u32_b32 v54, vcc_hi, v54
	v_lshl_add_u32 v55, v54, 2, s92
	v_cndmask_b32_e32 v55, v56, v55, vcc
	ds_write_b32 v55, v46 offset:8192
	v_bcnt_u32_b32 v54, vcc_lo, v53
	v_bcnt_u32_b32 v53, vcc_hi, v54
	v_cmp_ge_u32_e32 vcc, v43, v48
	s_nop 1
	v_mbcnt_lo_u32_b32 v54, vcc_lo, v53
	v_mbcnt_hi_u32_b32 v54, vcc_hi, v54
	v_lshl_add_u32 v55, v54, 2, s92
	v_cndmask_b32_e32 v55, v56, v55, vcc
	ds_write_b32 v55, v43 offset:8192
	v_bcnt_u32_b32 v54, vcc_lo, v53
	v_bcnt_u32_b32 v53, vcc_hi, v54
	v_cmp_ge_u32_e32 vcc, v44, v48
	s_nop 1
	v_mbcnt_lo_u32_b32 v54, vcc_lo, v53
	v_mbcnt_hi_u32_b32 v54, vcc_hi, v54
	v_lshl_add_u32 v55, v54, 2, s92
	v_cndmask_b32_e32 v55, v56, v55, vcc
	ds_write_b32 v55, v44 offset:8192
	v_bcnt_u32_b32 v54, vcc_lo, v53
	v_bcnt_u32_b32 v53, vcc_hi, v54
	v_cmp_ge_u32_e32 vcc, v41, v48
	s_nop 1
	v_mbcnt_lo_u32_b32 v54, vcc_lo, v53
	v_mbcnt_hi_u32_b32 v54, vcc_hi, v54
	v_lshl_add_u32 v55, v54, 2, s92
	v_cndmask_b32_e32 v55, v56, v55, vcc
	ds_write_b32 v55, v41 offset:8192
	v_bcnt_u32_b32 v54, vcc_lo, v53
	v_bcnt_u32_b32 v53, vcc_hi, v54
	v_cmp_ge_u32_e32 vcc, v42, v48
	s_nop 1
	v_mbcnt_lo_u32_b32 v54, vcc_lo, v53
	v_mbcnt_hi_u32_b32 v54, vcc_hi, v54
	v_lshl_add_u32 v55, v54, 2, s92
	v_cndmask_b32_e32 v55, v56, v55, vcc
	ds_write_b32 v55, v42 offset:8192
	v_bcnt_u32_b32 v54, vcc_lo, v53
	v_bcnt_u32_b32 v53, vcc_hi, v54
	v_cmp_ge_u32_e32 vcc, v39, v48
	s_nop 1
	v_mbcnt_lo_u32_b32 v54, vcc_lo, v53
	v_mbcnt_hi_u32_b32 v54, vcc_hi, v54
	v_lshl_add_u32 v55, v54, 2, s92
	v_cndmask_b32_e32 v55, v56, v55, vcc
	ds_write_b32 v55, v39 offset:8192
	v_bcnt_u32_b32 v54, vcc_lo, v53
	v_bcnt_u32_b32 v53, vcc_hi, v54
	v_cmp_ge_u32_e32 vcc, v40, v48
	s_nop 1
	v_mbcnt_lo_u32_b32 v54, vcc_lo, v53
	v_mbcnt_hi_u32_b32 v54, vcc_hi, v54
	v_lshl_add_u32 v55, v54, 2, s92
	v_cndmask_b32_e32 v55, v56, v55, vcc
	ds_write_b32 v55, v40 offset:8192
	v_bcnt_u32_b32 v54, vcc_lo, v53
	v_bcnt_u32_b32 v53, vcc_hi, v54
	v_cmp_ge_u32_e32 vcc, v37, v48
	s_nop 1
	v_mbcnt_lo_u32_b32 v54, vcc_lo, v53
	v_mbcnt_hi_u32_b32 v54, vcc_hi, v54
	v_lshl_add_u32 v55, v54, 2, s92
	v_cndmask_b32_e32 v55, v56, v55, vcc
	ds_write_b32 v55, v37 offset:8192
	v_bcnt_u32_b32 v54, vcc_lo, v53
	v_bcnt_u32_b32 v53, vcc_hi, v54
	v_cmp_ge_u32_e32 vcc, v38, v48
	s_nop 1
	v_mbcnt_lo_u32_b32 v54, vcc_lo, v53
	v_mbcnt_hi_u32_b32 v54, vcc_hi, v54
	v_lshl_add_u32 v55, v54, 2, s92
	v_cndmask_b32_e32 v55, v56, v55, vcc
	ds_write_b32 v55, v38 offset:8192
	v_bcnt_u32_b32 v54, vcc_lo, v53
	v_bcnt_u32_b32 v53, vcc_hi, v54
	v_cmp_ge_u32_e32 vcc, v36, v48
	s_nop 1
	v_mbcnt_lo_u32_b32 v54, vcc_lo, v53
	v_mbcnt_hi_u32_b32 v54, vcc_hi, v54
	v_lshl_add_u32 v55, v54, 2, s92
	v_cndmask_b32_e32 v55, v56, v55, vcc
	ds_write_b32 v55, v36 offset:8192
	v_bcnt_u32_b32 v54, vcc_lo, v53
	v_bcnt_u32_b32 v53, vcc_hi, v54
	s_nop 0
	v_readfirstlane_b32 s2, v53
	s_nop 1
	s_and_saveexec_b64 s[0:1], s[4:5]
	v_mov_b32_e32 v133, s2
	v_mov_b32_e32 v248, v48
	s_or_b64 exec, exec, s[0:1]

; __device__ __forceinline__ unsigned compact1024(unsigned* base, int n, int lane, int lowbit, int& newcnt) {
;     unsigned e[16];
; #pragma unroll
;     for (int j = 0; j < 16; ++j) { const int i = j * 64 + lane; e[j] = i < n ? base[i] : 0u; }
;     const unsigned tau = select_kth<16>(e, 256, lowbit);
;     const u64 lt = (1ull << lane) - 1ull; int run = 0;
; #pragma unroll
;     for (int j = 0; j < 16; ++j) { const bool p = e[j] >= tau; const u64 m = __ballot(p); if (p) base[run + __popcll(m & lt)] = e[j]; run += __popcll(m); }
;     newcnt = run;
.LBB0_1459:
	s_or_b64 exec, exec, s[0:1]
	v_mov_b32_e32 v53, 0
	v_mov_b32_e32 v56, s92
	v_add_u32_e32 v56, 0xffc, v56
	v_cmp_ge_u32_e32 vcc, v34, v48
	s_nop 1
	v_mbcnt_lo_u32_b32 v54, vcc_lo, v53
	v_mbcnt_hi_u32_b32 v54, vcc_hi, v54
	v_lshl_add_u32 v55, v54, 2, s92
	v_cndmask_b32_e32 v55, v56, v55, vcc
	ds_write_b32 v55, v34 offset:12288
	v_bcnt_u32_b32 v54, vcc_lo, v53
	v_bcnt_u32_b32 v53, vcc_hi, v54
	v_cmp_ge_u32_e32 vcc, v35, v48
	s_nop 1
	v_mbcnt_lo_u32_b32 v54, vcc_lo, v53
	v_mbcnt_hi_u32_b32 v54, vcc_hi, v54
	v_lshl_add_u32 v55, v54, 2, s92
	v_cndmask_b32_e32 v55, v56, v55, vcc
	ds_write_b32 v55, v35 offset:12288
	v_bcnt_u32_b32 v54, vcc_lo, v53
	v_bcnt_u32_b32 v53, vcc_hi, v54
	v_cmp_ge_u32_e32 vcc, v32, v48
	s_nop 1
	v_mbcnt_lo_u32_b32 v54, vcc_lo, v53
	v_mbcnt_hi_u32_b32 v54, vcc_hi, v54
	v_lshl_add_u32 v55, v54, 2, s92
	v_cndmask_b32_e32 v55, v56, v55, vcc
	ds_write_b32 v55, v32 offset:12288
	v_bcnt_u32_b32 v54, vcc_lo, v53
	v_bcnt_u32_b32 v53, vcc_hi, v54
	v_cmp_ge_u32_e32 vcc, v33, v48
	s_nop 1
	v_mbcnt_lo_u32_b32 v54, vcc_lo, v53
	v_mbcnt_hi_u32_b32 v54, vcc_hi, v54
	v_lshl_add_u32 v55, v54, 2, s92
	v_cndmask_b32_e32 v55, v56, v55, vcc
	ds_write_b32 v55, v33 offset:12288
	v_bcnt_u32_b32 v54, vcc_lo, v53
	v_bcnt_u32_b32 v53, vcc_hi, v54
	v_cmp_ge_u32_e32 vcc, v47, v48
	s_nop 1
	v_mbcnt_lo_u32_b32 v54, vcc_lo, v53
	v_mbcnt_hi_u32_b32 v54, vcc_hi, v54
	v_lshl_add_u32 v55, v54, 2, s92
	v_cndmask_b32_e32 v55, v56, v55, vcc
	ds_write_b32 v55, v47 offset:12288
	v_bcnt_u32_b32 v54, vcc_lo, v53
	v_bcnt_u32_b32 v53, vcc_hi, v54
	v_cmp_ge_u32_e32 vcc, v45, v48
	s_nop 1
	v_mbcnt_lo_u32_b32 v54, vcc_lo, v53
	v_mbcnt_hi_u32_b32 v54, vcc_hi, v54
	v_lshl_add_u32 v55, v54, 2, s92
	v_cndmask_b32_e32 v55, v56, v55, vcc
	ds_write_b32 v55, v45 offset:12288
	v_bcnt_u32_b32 v54, vcc_lo, v53
	v_bcnt_u32_b32 v53, vcc_hi, v54
	v_cmp_ge_u32_e32 vcc, v46, v48
	s_nop 1
	v_mbcnt_lo_u32_b32 v54, vcc_lo, v53
	v_mbcnt_hi_u32_b32 v54, vcc_hi, v54
	v_lshl_add_u32 v55, v54, 2, s92
	v_cndmask_b32_e32 v55, v56, v55, vcc
	ds_write_b32 v55, v46 offset:12288
	v_bcnt_u32_b32 v54, vcc_lo, v53
	v_bcnt_u32_b32 v53, vcc_hi, v54
	v_cmp_ge_u32_e32 vcc, v43, v48
	s_nop 1
	v_mbcnt_lo_u32_b32 v54, vcc_lo, v53
	v_mbcnt_hi_u32_b32 v54, vcc_hi, v54
	v_lshl_add_u32 v55, v54, 2, s92
	v_cndmask_b32_e32 v55, v56, v55, vcc
	ds_write_b32 v55, v43 offset:12288
	v_bcnt_u32_b32 v54, vcc_lo, v53
	v_bcnt_u32_b32 v53, vcc_hi, v54
	v_cmp_ge_u32_e32 vcc, v44, v48
	s_nop 1
	v_mbcnt_lo_u32_b32 v54, vcc_lo, v53
	v_mbcnt_hi_u32_b32 v54, vcc_hi, v54
	v_lshl_add_u32 v55, v54, 2, s92
	v_cndmask_b32_e32 v55, v56, v55, vcc
	ds_write_b32 v55, v44 offset:12288
	v_bcnt_u32_b32 v54, vcc_lo, v53
	v_bcnt_u32_b32 v53, vcc_hi, v54
	v_cmp_ge_u32_e32 vcc, v41, v48
	s_nop 1
	v_mbcnt_lo_u32_b32 v54, vcc_lo, v53
	v_mbcnt_hi_u32_b32 v54, vcc_hi, v54
	v_lshl_add_u32 v55, v54, 2, s92
	v_cndmask_b32_e32 v55, v56, v55, vcc
	ds_write_b32 v55, v41 offset:12288
	v_bcnt_u32_b32 v54, vcc_lo, v53
	v_bcnt_u32_b32 v53, vcc_hi, v54
	v_cmp_ge_u32_e32 vcc, v42, v48
	s_nop 1
	v_mbcnt_lo_u32_b32 v54, vcc_lo, v53
	v_mbcnt_hi_u32_b32 v54, vcc_hi, v54
	v_lshl_add_u32 v55, v54, 2, s92
	v_cndmask_b32_e32 v55, v56, v55, vcc
	ds_write_b32 v55, v42 offset:12288
	v_bcnt_u32_b32 v54, vcc_lo, v53
	v_bcnt_u32_b32 v53, vcc_hi, v54
	v_cmp_ge_u32_e32 vcc, v39, v48
	s_nop 1
	v_mbcnt_lo_u32_b32 v54, vcc_lo, v53
	v_mbcnt_hi_u32_b32 v54, vcc_hi, v54
	v_lshl_add_u32 v55, v54, 2, s92
	v_cndmask_b32_e32 v55, v56, v55, vcc
	ds_write_b32 v55, v39 offset:12288
	v_bcnt_u32_b32 v54, vcc_lo, v53
	v_bcnt_u32_b32 v53, vcc_hi, v54
	v_cmp_ge_u32_e32 vcc, v40, v48
	s_nop 1
	v_mbcnt_lo_u32_b32 v54, vcc_lo, v53
	v_mbcnt_hi_u32_b32 v54, vcc_hi, v54
	v_lshl_add_u32 v55, v54, 2, s92
	v_cndmask_b32_e32 v55, v56, v55, vcc
	ds_write_b32 v55, v40 offset:12288
	v_bcnt_u32_b32 v54, vcc_lo, v53
	v_bcnt_u32_b32 v53, vcc_hi, v54
	v_cmp_ge_u32_e32 vcc, v37, v48
	s_nop 1
	v_mbcnt_lo_u32_b32 v54, vcc_lo, v53
	v_mbcnt_hi_u32_b32 v54, vcc_hi, v54
	v_lshl_add_u32 v55, v54, 2, s92
	v_cndmask_b32_e32 v55, v56, v55, vcc
	ds_write_b32 v55, v37 offset:12288
	v_bcnt_u32_b32 v54, vcc_lo, v53
	v_bcnt_u32_b32 v53, vcc_hi, v54
	v_cmp_ge_u32_e32 vcc, v38, v48
	s_nop 1
	v_mbcnt_lo_u32_b32 v54, vcc_lo, v53
	v_mbcnt_hi_u32_b32 v54, vcc_hi, v54
	v_lshl_add_u32 v55, v54, 2, s92
	v_cndmask_b32_e32 v55, v56, v55, vcc
	ds_write_b32 v55, v38 offset:12288
	v_bcnt_u32_b32 v54, vcc_lo, v53
	v_bcnt_u32_b32 v53, vcc_hi, v54
	v_cmp_ge_u32_e32 vcc, v36, v48
	s_nop 1
	v_mbcnt_lo_u32_b32 v54, vcc_lo, v53
	v_mbcnt_hi_u32_b32 v54, vcc_hi, v54
	v_lshl_add_u32 v55, v54, 2, s92
	v_cndmask_b32_e32 v55, v56, v55, vcc
	ds_write_b32 v55, v36 offset:12288
	v_bcnt_u32_b32 v54, vcc_lo, v53
	v_bcnt_u32_b32 v53, vcc_hi, v54
	s_nop 0
	v_readfirstlane_b32 s2, v53
	s_nop 1
	s_and_saveexec_b64 s[0:1], s[6:7]
	v_mov_b32_e32 v133, s2
	v_mov_b32_e32 v248, v48
	s_or_b64 exec, exec, s[0:1]
